# LayerNorm row loop: loop-invariant vmcnt(0) drain hoisted to the preheader, counted wait at the latch so stores and next-row loads stay in flight, DPP wave reductions instead of ds_bpermute chains
# speedup vs baseline: 1.0060x; 1.0060x over previous
; __device__ __forceinline__ void ln_rows(bf16* XH, unsigned char* XQ, float* XS, float* VST, float* OUT, const float* g, const float* bta, bool last, int gw, int NGW, int lane) {
;     f32x4 gv[4], bv[4];
; #pragma unroll
;     for (int j = 0; j < 2; ++j) { gv[2 * j] = *(const f32x4*)(g + 512 * j + lane * 8); gv[2 * j + 1] = *(const f32x4*)(g + 512 * j + lane * 8 + 4);
;                                   bv[2 * j] = *(const f32x4*)(bta + 512 * j + lane * 8); bv[2 * j + 1] = *(const f32x4*)(bta + 512 * j + lane * 8 + 4); }
;     u32x4 nx0 = *(const u32x4*)(XH + (size_t)gw * DM + lane * 8), nx1 = *(const u32x4*)(XH + (size_t)gw * DM + lane * 8 + 512);
;     for (int m = gw; m < T; m += NGW) {
;         bf16* xr = XH + (size_t)m * DM + lane * 8;
;         f32x4 v[4]; float s = 0.f;
;         const u32x4 cx0 = nx0, cx1 = nx1;
;         if (m + NGW < T) { nx0 = *(const u32x4*)(xr + (size_t)NGW * DM); nx1 = *(const u32x4*)(xr + (size_t)NGW * DM + 512); }
.LBB0_972:
	s_or_b64 exec, exec, s[0:1]
	s_waitcnt lgkmcnt(0)
	v_mov_b32_e32 v0, v232
	s_barrier
	v_readlane_b32 s1, v252, 35
	v_readfirstlane_b32 s0, v0
	s_ashr_i32 s0, s0, 6
	s_add_i32 s2, s0, s1
	s_cmp_eq_u32 s6, 4
	s_cselect_b64 s[0:1], -1, 0
	s_cmp_lg_u32 s6, 4
	s_mov_b64 s[4:5], 0x1ed00000
	s_cselect_b64 s[8:9], -1, 0
	s_cmpk_gt_i32 s2, 0x7fff
	s_cbranch_scc1 .LBB0_983
	v_readlane_b32 s44, v252, 1
	v_readlane_b32 s58, v252, 15
	v_readlane_b32 s59, v252, 16
	s_add_u32 s7, s58, s4
	v_readlane_b32 s52, v252, 9
	s_addc_u32 s14, s59, s5
	v_readlane_b32 s12, v255, 23
	v_readlane_b32 s53, v252, 10
	v_readlane_b32 s13, v255, 24
	s_add_u32 s10, s52, s12
	v_and_b32_e32 v32, 63, v0
	v_readlane_b32 s54, v252, 11
	s_addc_u32 s11, s53, s13
	v_readlane_b32 s55, v252, 12
	s_add_u32 s12, s54, s12
	v_lshlrev_b32_e32 v33, 5, v32
	s_addc_u32 s13, s55, s13
	global_load_dwordx4 v[0:3], v33, s[10:11] offset:16
	global_load_dwordx4 v[4:7], v33, s[10:11]
	global_load_dwordx4 v[8:11], v33, s[12:13] offset:16
	global_load_dwordx4 v[12:15], v33, s[12:13]
	global_load_dwordx4 v[16:19], v33, s[10:11] offset:2064
	global_load_dwordx4 v[20:23], v33, s[10:11] offset:2048
	s_ashr_i32 s3, s2, 31
	s_lshl_b64 s[18:19], s[2:3], 11
	s_add_u32 s10, s7, s18
	s_addc_u32 s11, s14, s19
	v_lshlrev_b32_e32 v64, 4, v32
	global_load_dwordx4 v[40:43], v64, s[10:11] offset:1024
	global_load_dwordx4 v[44:47], v64, s[10:11]
	global_load_dwordx4 v[24:27], v33, s[12:13] offset:2064
	global_load_dwordx4 v[28:31], v33, s[12:13] offset:2048
	s_lshl_b64 s[10:11], s[2:3], 2
	s_add_u32 s7, s10, 0x22d00000
	v_and_b32_e32 v34, 64, v236
	s_addc_u32 s10, s11, 0
	s_lshl_b64 s[12:13], s[2:3], 3
	v_xor_b32_e32 v35, 1, v236
	v_add_u32_e32 v34, 64, v34
	s_add_u32 s11, s12, 0x22d80000
	v_xor_b32_e32 v36, 2, v236
	v_cmp_lt_i32_e32 vcc, v35, v34
	s_addc_u32 s14, s13, 0
	s_lshl_b64 s[12:13], s[2:3], 10
	v_xor_b32_e32 v37, 4, v236
	v_cndmask_b32_e32 v35, v236, v35, vcc
	v_cmp_lt_i32_e32 vcc, v36, v34
	v_lshl_or_b32 v56, v32, 3, s12
	s_add_u32 s12, s4, s18
	v_xor_b32_e32 v38, 8, v236
	v_cndmask_b32_e32 v36, v236, v36, vcc
	v_cmp_lt_i32_e32 vcc, v37, v34
	v_mov_b32_e32 v57, s13
	s_addc_u32 s13, s5, s19
	v_readlane_b32 s4, v254, 51
	v_xor_b32_e32 v39, 16, v236
	v_cndmask_b32_e32 v37, v236, v37, vcc
	v_cmp_lt_i32_e32 vcc, v38, v34
	s_add_u32 s4, s12, s4
	v_readlane_b32 s5, v254, 54
	v_xor_b32_e32 v48, 32, v236
	v_cndmask_b32_e32 v38, v236, v38, vcc
	v_cmp_lt_i32_e32 vcc, v39, v34
	s_addc_u32 s5, s13, s5
	v_lshl_add_u64 v[58:59], s[4:5], 0, v[64:65]
	v_cndmask_b32_e32 v39, v236, v39, vcc
	v_cmp_lt_i32_e32 vcc, v48, v34
	s_add_u32 s4, s12, 0x400
	s_addc_u32 s5, s13, 0
	v_cndmask_b32_e32 v34, v236, v48, vcc
	s_lshl_b64 s[12:13], s[2:3], 12
	v_cmp_eq_u32_e64 s[36:37], 0, v32
	v_lshlrev_b32_e32 v66, 2, v35
	v_lshlrev_b32_e32 v67, 2, v36
	v_lshlrev_b32_e32 v68, 2, v37
	v_lshlrev_b32_e32 v69, 2, v38
	v_lshlrev_b32_e32 v70, 2, v39
	v_lshlrev_b32_e32 v71, 2, v34
	v_or_b32_e32 v62, s12, v33
	v_lshl_add_u64 v[60:61], s[4:5], 0, v[64:65]
	v_mov_b32_e32 v63, s13
	v_readlane_b32 s45, v252, 2
	v_readlane_b32 s46, v252, 3
	v_readlane_b32 s47, v252, 4
	v_readlane_b32 s48, v252, 5
	v_readlane_b32 s49, v252, 6
	v_readlane_b32 s50, v252, 7
	v_readlane_b32 s51, v252, 8
	v_readlane_b32 s56, v252, 13
	v_readlane_b32 s57, v252, 14
	s_waitcnt vmcnt(3)
	v_mov_b64_e32 v[32:33], v[40:41]
	s_waitcnt vmcnt(0)
	v_mov_b64_e32 v[36:37], v[44:45]
	v_mov_b64_e32 v[34:35], v[42:43]
	v_mov_b64_e32 v[38:39], v[46:47]
	s_branch .LBB0_975
.LBB0_974:
	s_waitcnt vmcnt(4)
	v_readlane_b32 s4, v255, 0
	v_readlane_b32 s5, v255, 1
	s_add_u32 s7, s7, s4
	s_addc_u32 s10, s10, s5
	v_readlane_b32 s4, v255, 2
	v_readlane_b32 s5, v255, 3
	s_add_u32 s11, s11, s4
	s_addc_u32 s14, s14, s5
	v_readlane_b32 s4, v255, 4
	v_readlane_b32 s5, v255, 5
	v_mov_b64_e32 v[46:47], v[38:39]
	v_mov_b64_e32 v[42:43], v[34:35]
	v_lshl_add_u64 v[56:57], v[56:57], 0, s[4:5]
	v_readlane_b32 s4, v254, 52
	v_readlane_b32 s5, v254, 53
	s_andn2_b64 vcc, exec, s[12:13]
	v_mov_b64_e32 v[44:45], v[36:37]
	v_lshl_add_u64 v[58:59], v[58:59], 0, s[4:5]
	v_lshl_add_u64 v[60:61], v[60:61], 0, s[4:5]
	v_readlane_b32 s4, v255, 8
	v_readlane_b32 s5, v255, 9
	v_mov_b64_e32 v[40:41], v[32:33]
	s_nop 0
	v_lshl_add_u64 v[62:63], v[62:63], 0, s[4:5]
	s_cbranch_vccz .LBB0_983

; __device__ __forceinline__ float wave_sum(float v) {
; #pragma unroll
;     for (int o = 1; o < 64; o <<= 1) v += __shfl_xor(v, o);
;     return v;
; }
; __device__ __forceinline__ void ln_rows(bf16* XH, unsigned char* XQ, float* XS, float* VST, float* OUT, const float* g, const float* bta, bool last, int gw, int NGW, int lane) {
;     ...
;         pg8::unpack8h(cx0, v[0], v[1]); pg8::unpack8h(cx1, v[2], v[3]);
; #pragma unroll
;         for (int j = 0; j < 4; ++j) s += (v[j][0] + v[j][1]) + (v[j][2] + v[j][3]);
;         const float mean = wave_sum(s) * (1.f / DM); float s2 = 0.f;
; #pragma unroll
;         for (int j = 0; j < 4; ++j) { v[j] = v[j] - mean; s2 += (v[j][0] * v[j][0] + v[j][1] * v[j][1]) + (v[j][2] * v[j][2] + v[j][3] * v[j][3]); }
;         const float rstd = 1.0f / sqrtf(wave_sum(s2) * (1.f / DM) + LN_EPS);
; #pragma unroll
;         for (int j = 0; j < 4; ++j) v[j] = v[j] * rstd * gv[j] + bv[j];
.LBB0_977:
	v_cvt_f32_f16_sdwa v48, v44 dst_sel:DWORD dst_unused:UNUSED_PAD src0_sel:WORD_1
	v_cvt_f32_f16_e32 v50, v44
	v_cvt_f32_f16_sdwa v49, v45 dst_sel:DWORD dst_unused:UNUSED_PAD src0_sel:WORD_1
	v_cvt_f32_f16_e32 v51, v45
	v_cvt_f32_f16_sdwa v52, v46 dst_sel:DWORD dst_unused:UNUSED_PAD src0_sel:WORD_1
	v_cvt_f32_f16_e32 v54, v46
	v_cvt_f32_f16_sdwa v53, v47 dst_sel:DWORD dst_unused:UNUSED_PAD src0_sel:WORD_1
	v_cvt_f32_f16_e32 v55, v47
	v_cvt_f32_f16_sdwa v64, v40 dst_sel:DWORD dst_unused:UNUSED_PAD src0_sel:WORD_1
	v_cvt_f32_f16_e32 v73, v40
	v_cvt_f32_f16_sdwa v79, v41 dst_sel:DWORD dst_unused:UNUSED_PAD src0_sel:WORD_1
	v_cvt_f32_f16_e32 v80, v41
	v_pk_add_f32 v[48:49], v[50:51], v[48:49]
	v_cvt_f32_f16_sdwa v72, v42 dst_sel:DWORD dst_unused:UNUSED_PAD src0_sel:WORD_1
	v_cvt_f32_f16_e32 v74, v42
	v_cvt_f32_f16_sdwa v76, v43 dst_sel:DWORD dst_unused:UNUSED_PAD src0_sel:WORD_1
	v_cvt_f32_f16_e32 v78, v43
	v_add_f32_e32 v48, v48, v49
	v_add_f32_e32 v77, 0, v48
	v_pk_add_f32 v[48:49], v[54:55], v[52:53]
	v_add_f32_e32 v75, v73, v64
	v_pk_add_f32 v[48:49], v[48:49], v[48:49] op_sel_hi:[0,1]
	v_add_f32_e32 v73, v80, v79
	v_mov_b32_e32 v79, v49
	v_pk_add_f32 v[50:51], v[74:75], v[72:73]
	v_pk_add_f32 v[48:49], v[78:79], v[76:77]
	s_mov_b32 s3, 0xba800000
	v_pk_add_f32 v[48:49], v[50:51], v[48:49]
	s_nop 0
	v_add_f32_e32 v48, v48, v49
	s_nop 1
	v_add_f32_dpp v48, v48, v48 quad_perm:[1,0,3,2] row_mask:0xf bank_mask:0xf
	s_nop 1
	v_add_f32_dpp v48, v48, v48 quad_perm:[2,3,0,1] row_mask:0xf bank_mask:0xf
	s_nop 1
	v_add_f32_dpp v48, v48, v48 row_half_mirror row_mask:0xf bank_mask:0xf
	s_nop 1
	v_add_f32_dpp v48, v48, v48 row_mirror row_mask:0xf bank_mask:0xf
	s_nop 1
	v_add_f32_dpp v48, v48, v48 row_bcast:15 row_mask:0xa bank_mask:0xf
	s_nop 1
	v_add_f32_dpp v48, v48, v48 row_bcast:31 row_mask:0xc bank_mask:0xf
	s_nop 1
	v_readlane_b32 s98, v48, 63
	s_nop 1
	v_mov_b32_e32 v64, s98
	v_fma_mix_f32 v49, v64, s3, v44 op_sel:[0,0,1] op_sel_hi:[0,0,1]
	v_fma_mix_f32 v48, v64, s3, v44 op_sel_hi:[0,0,1]
	v_fma_mix_f32 v51, v64, s3, v45 op_sel:[0,0,1] op_sel_hi:[0,0,1]
	v_fma_mix_f32 v50, v64, s3, v45 op_sel_hi:[0,0,1]
	v_pk_mul_f32 v[52:53], v[50:51], v[50:51]
	v_pk_mul_f32 v[54:55], v[48:49], v[48:49]
	v_fma_mix_f32 v45, v64, s3, v46 op_sel:[0,0,1] op_sel_hi:[0,0,1]
	v_pk_mov_b32 v[72:73], v[54:55], v[52:53] op_sel:[1,0]
	v_mov_b32_e32 v55, v53
	v_pk_add_f32 v[52:53], v[72:73], v[54:55]
	v_fma_mix_f32 v44, v64, s3, v46 op_sel_hi:[0,0,1]
	v_fma_mix_f32 v55, v64, s3, v47 op_sel:[0,0,1] op_sel_hi:[0,0,1]
	v_fma_mix_f32 v54, v64, s3, v47 op_sel_hi:[0,0,1]
	v_pk_mul_f32 v[46:47], v[54:55], v[54:55]
	v_pk_mul_f32 v[72:73], v[44:45], v[44:45]
	v_pk_add_f32 v[52:53], v[52:53], v[52:53] op_sel_hi:[0,1]
	v_pk_mov_b32 v[74:75], v[72:73], v[46:47] op_sel:[1,0]
	v_mov_b32_e32 v73, v47
	v_pk_add_f32 v[46:47], v[74:75], v[72:73]
	v_fma_mix_f32 v72, v64, s3, v40 op_sel_hi:[0,0,1]
	v_fma_mix_f32 v73, v64, s3, v40 op_sel:[0,0,1] op_sel_hi:[0,0,1]
	v_mul_f32_e32 v40, v72, v72
	v_fma_mix_f32 v75, v64, s3, v41 op_sel:[0,0,1] op_sel_hi:[0,0,1]
	v_fma_mix_f32 v74, v64, s3, v41 op_sel_hi:[0,0,1]
	v_pk_fma_f32 v[40:41], v[72:73], v[72:73], v[40:41] op_sel_hi:[1,1,0]
	v_pk_add_f32 v[46:47], v[46:47], v[46:47] op_sel_hi:[0,1]
	v_mul_f32_e32 v40, v74, v74
	v_pk_fma_f32 v[76:77], v[74:75], v[74:75], v[40:41] op_sel_hi:[1,1,0]
	v_fma_mix_f32 v79, v64, s3, v43 op_sel:[0,0,1] op_sel_hi:[0,0,1]
	v_fma_mix_f32 v78, v64, s3, v43 op_sel_hi:[0,0,1]
	v_fma_mix_f32 v81, v64, s3, v42 op_sel:[0,0,1] op_sel_hi:[0,0,1]
	v_fma_mix_f32 v80, v64, s3, v42 op_sel_hi:[0,0,1]
	v_mul_f32_e32 v40, v80, v80
	v_mul_f32_e32 v76, v81, v81
	v_mul_f32_e32 v52, v78, v78
	v_mul_f32_e32 v46, v79, v79
	v_pk_add_f32 v[40:41], v[40:41], v[76:77]
	v_pk_add_f32 v[42:43], v[52:53], v[46:47]
	s_mov_b32 s3, 0xf800000
	v_pk_add_f32 v[40:41], v[40:41], v[42:43]
	s_nop 0
	v_add_f32_e32 v40, v40, v41
	s_nop 1
	v_add_f32_dpp v40, v40, v40 quad_perm:[1,0,3,2] row_mask:0xf bank_mask:0xf
	s_nop 1
	v_add_f32_dpp v40, v40, v40 quad_perm:[2,3,0,1] row_mask:0xf bank_mask:0xf
	s_nop 1
	v_add_f32_dpp v40, v40, v40 row_half_mirror row_mask:0xf bank_mask:0xf
	s_nop 1
	v_add_f32_dpp v40, v40, v40 row_mirror row_mask:0xf bank_mask:0xf
	s_nop 1
	v_add_f32_dpp v40, v40, v40 row_bcast:15 row_mask:0xa bank_mask:0xf
	s_nop 1
	v_add_f32_dpp v40, v40, v40 row_bcast:31 row_mask:0xc bank_mask:0xf
	s_nop 1
	v_readlane_b32 s98, v40, 63
	s_nop 1
	v_mov_b32_e32 v40, s98
	v_fmamk_f32 v40, v40, 0x3a800000, v235
	v_mul_f32_e32 v41, 0x4f800000, v40
	v_cmp_gt_f32_e32 vcc, s3, v40
	s_nop 1
	v_cndmask_b32_e32 v40, v40, v41, vcc
	v_sqrt_f32_e32 v41, v40
	s_nop 0
	v_add_u32_e32 v42, -1, v41
	v_fma_f32 v43, -v42, v41, v40
	v_cmp_ge_f32_e64 s[4:5], 0, v43
	v_add_u32_e32 v43, 1, v41
	s_nop 0
	v_cndmask_b32_e64 v42, v41, v42, s[4:5]
	v_fma_f32 v41, -v43, v41, v40
	v_cmp_lt_f32_e64 s[4:5], 0, v41
	s_nop 1
	v_cndmask_b32_e64 v41, v42, v43, s[4:5]
	v_mul_f32_e32 v42, 0x37800000, v41
	v_cndmask_b32_e32 v41, v41, v42, vcc
	v_cmp_class_f32_e32 vcc, v40, v234
	s_nop 1
	v_cndmask_b32_e32 v40, v41, v40, vcc
	v_div_scale_f32 v41, s[4:5], v40, v40, 1.0
	v_rcp_f32_e32 v42, v41
	s_mov_b64 s[4:5], -1
	v_fma_f32 v43, -v41, v42, 1.0
	v_fmac_f32_e32 v42, v43, v42
	v_div_scale_f32 v43, vcc, 1.0, v40, 1.0
	v_mul_f32_e32 v46, v43, v42
	v_fma_f32 v47, -v41, v46, v43
	v_fmac_f32_e32 v46, v47, v42
	v_fma_f32 v41, -v41, v46, v43
	v_div_fmas_f32 v41, v41, v42, v46
	v_div_fixup_f32 v52, v41, v40, 1.0
	v_pk_mul_f32 v[40:41], v[48:49], v[52:53] op_sel_hi:[1,0]
	v_pk_mul_f32 v[42:43], v[50:51], v[52:53] op_sel_hi:[1,0]
	v_pk_mul_f32 v[44:45], v[44:45], v[52:53] op_sel_hi:[1,0]
	v_pk_mul_f32 v[46:47], v[54:55], v[52:53] op_sel_hi:[1,0]
	v_pk_mul_f32 v[48:49], v[72:73], v[52:53] op_sel_hi:[1,0]
	v_pk_mul_f32 v[50:51], v[74:75], v[52:53] op_sel_hi:[1,0]
	v_pk_mul_f32 v[72:73], v[80:81], v[52:53] op_sel_hi:[1,0]
	v_pk_mul_f32 v[52:53], v[78:79], v[52:53] op_sel_hi:[1,0]
	v_pk_fma_f32 v[42:43], v[6:7], v[42:43], v[14:15]
	v_pk_fma_f32 v[40:41], v[4:5], v[40:41], v[12:13]
	v_pk_fma_f32 v[46:47], v[2:3], v[46:47], v[10:11]
	v_pk_fma_f32 v[44:45], v[0:1], v[44:45], v[8:9]
	v_pk_fma_f32 v[50:51], v[22:23], v[50:51], v[30:31]
	v_pk_fma_f32 v[48:49], v[20:21], v[48:49], v[28:29]
	v_pk_fma_f32 v[54:55], v[18:19], v[52:53], v[26:27]
	v_pk_fma_f32 v[52:53], v[16:17], v[72:73], v[24:25]
	s_and_b64 vcc, exec, s[8:9]
	s_cbranch_vccz .LBB0_981
; __device__ __forceinline__ u32x4 pack8h(const f32x4 a, const f32x4 b) { u32x4 w; w.x = cvt_pk_f16(a[0], a[1]); w.y = cvt_pk_f16(a[2], a[3]); w.z = cvt_pk_f16(b[0], b[1]); w.w = cvt_pk_f16(b[2], b[3]); return w; }
; __device__ __forceinline__ float wave_max(float v) {
; #pragma unroll
;     for (int o = 1; o < 64; o <<= 1) v = fmaxf(v, __shfl_xor(v, o));
;     return v;
; }
; __device__ __forceinline__ void ln_rows(bf16* XH, unsigned char* XQ, float* XS, float* VST, float* OUT, const float* g, const float* bta, bool last, int gw, int NGW, int lane) {
;     ...
;         if (last) { float* o = OUT + (size_t)m * DM + lane * 8;
;             *(f32x4*)o = v[0]; *(f32x4*)(o + 4) = v[1]; *(f32x4*)(o + 512) = v[2]; *(f32x4*)(o + 516) = v[3]; }
;         else { *(u32x4*)xr = pg8::pack8h(v[0], v[1]); *(u32x4*)(xr + 512) = pg8::pack8h(v[2], v[3]);
;             float am = 0.f;
; #pragma unroll
;             for (int j = 0; j < 4; ++j) am = fmaxf(am, fmaxf(fmaxf(fabsf(v[j][0]), fabsf(v[j][1])), fmaxf(fabsf(v[j][2]), fabsf(v[j][3]))));
;             am = wave_max(am); const float inv = am > 0.f ? 127.f / am : 0.f;
;             unsigned char* xq = XQ + (size_t)m * DM + lane * 8;
;             u32x2 w0, w1; w0.x = q4(v[0][0], v[0][1], v[0][2], v[0][3], inv); w0.y = q4(v[1][0], v[1][1], v[1][2], v[1][3], inv);
;             w1.x = q4(v[2][0], v[2][1], v[2][2], v[2][3], inv); w1.y = q4(v[3][0], v[3][1], v[3][2], v[3][3], inv);
;             *(u32x2*)xq = w0; *(u32x2*)(xq + 512) = w1; if (lane == 0) { XS[m] = am; VST[2 * (size_t)m] = 0.f; VST[2 * (size_t)m + 1] = 0.f; } }
	v_readlane_b32 s44, v252, 1
	v_readlane_b32 s58, v252, 15
	v_readlane_b32 s59, v252, 16
	v_cvt_pk_f16_f32 v72, v40, v41
	v_cvt_pk_f16_f32 v73, v42, v43
	v_lshl_add_u64 v[76:77], s[58:59], 0, v[60:61]
	v_cvt_pk_f16_f32 v74, v44, v45
	v_cvt_pk_f16_f32 v75, v46, v47
	global_store_dwordx4 v[76:77], v[72:75], off offset:-1024
	v_max_f32_e64 v64, |v43|, |v43|
	s_mov_b32 s3, 0x42fe0000
	v_cvt_pk_f16_f32 v72, v48, v49
	v_cvt_pk_f16_f32 v73, v50, v51
	v_cvt_pk_f16_f32 v74, v52, v53
	v_cvt_pk_f16_f32 v75, v54, v55
	global_store_dwordx4 v[76:77], v[72:75], off
	v_readlane_b32 s56, v252, 13
	v_readlane_b32 s57, v252, 14
	v_max_f32_e64 v72, |v42|, |v42|
	v_max_f32_e32 v64, v72, v64
	v_max_f32_e64 v72, |v47|, |v47|
	v_max_f32_e64 v73, |v46|, |v46|
	v_max_f32_e32 v72, v73, v72
	v_max3_f32 v64, |v40|, |v41|, v64
	v_max3_f32 v72, |v44|, |v45|, v72
	v_max3_f32 v64, v64, 0, v72
	v_max_f32_e64 v72, |v51|, |v51|
	v_max_f32_e64 v73, |v50|, |v50|
	v_max_f32_e32 v72, v73, v72
	v_max_f32_e64 v73, |v55|, |v55|
	v_max_f32_e64 v74, |v54|, |v54|
	v_max_f32_e32 v73, v74, v73
	v_max3_f32 v72, |v48|, |v49|, v72
	v_max3_f32 v73, |v52|, |v53|, v73
	v_max3_f32 v64, v64, v72, v73
	v_readlane_b32 s45, v252, 2
	v_readlane_b32 s46, v252, 3
	v_readlane_b32 s47, v252, 4
	v_readlane_b32 s48, v252, 5
	v_readlane_b32 s49, v252, 6
	v_readlane_b32 s50, v252, 7
	v_readlane_b32 s51, v252, 8
	v_readlane_b32 s52, v252, 9
	v_readlane_b32 s53, v252, 10
	v_readlane_b32 s54, v252, 11
	v_readlane_b32 s55, v252, 12
	s_nop 1
	v_max_f32_dpp v64, v64, v64 quad_perm:[1,0,3,2] row_mask:0xf bank_mask:0xf
	s_nop 1
	v_max_f32_dpp v64, v64, v64 quad_perm:[2,3,0,1] row_mask:0xf bank_mask:0xf
	s_nop 1
	v_max_f32_dpp v64, v64, v64 row_half_mirror row_mask:0xf bank_mask:0xf
	s_nop 1
	v_max_f32_dpp v64, v64, v64 row_mirror row_mask:0xf bank_mask:0xf
	s_nop 1
	v_max_f32_dpp v64, v64, v64 row_bcast:15 row_mask:0xa bank_mask:0xf
	s_nop 1
	v_max_f32_dpp v64, v64, v64 row_bcast:31 row_mask:0xc bank_mask:0xf
	s_nop 1
	v_readlane_b32 s98, v64, 63
	s_nop 1
	v_mov_b32_e32 v64, s98
	v_div_scale_f32 v72, s[18:19], v64, v64, s3
	v_rcp_f32_e32 v73, v72
	v_cmp_lt_f32_e64 s[4:5], 0, v64
	v_fma_f32 v74, -v72, v73, 1.0
	v_fmac_f32_e32 v73, v74, v73
	v_div_scale_f32 v74, vcc, s3, v64, s3
	v_mul_f32_e32 v75, v74, v73
	v_fma_f32 v76, -v72, v75, v74
	v_fmac_f32_e32 v75, v76, v73
	v_fma_f32 v72, -v72, v75, v74
	v_div_fmas_f32 v72, v72, v73, v75
	v_div_fixup_f32 v72, v72, v64, s3
	v_cndmask_b32_e64 v77, 0, v72, s[4:5]
	v_mul_f32_e32 v75, v41, v77
	v_mul_f32_e32 v74, v40, v77
	v_rndne_f32_e32 v75, v75
	v_mul_f32_e32 v76, v42, v77
	v_mul_f32_e32 v78, v43, v77
	v_rndne_f32_e32 v74, v74
	v_cvt_i32_f32_e32 v75, v75
	v_rndne_f32_e32 v76, v76
	v_rndne_f32_e32 v78, v78
	v_cvt_i32_f32_e32 v74, v74
	v_cvt_i32_f32_sdwa v76, v76 dst_sel:WORD_1 dst_unused:UNUSED_PAD src0_sel:DWORD
	v_cvt_i32_f32_e32 v78, v78
	v_lshlrev_b32_e32 v75, 8, v75
	s_mov_b32 s3, 0x40c0c00
	v_and_b32_e32 v75, 0xff00, v75
	v_and_b32_e32 v76, 0xff0000, v76
	v_perm_b32 v74, v78, v74, s3
	v_or3_b32 v74, v74, v75, v76
	v_mul_f32_e32 v76, v45, v77
	v_mul_f32_e32 v75, v44, v77
	v_rndne_f32_e32 v76, v76
	v_mul_f32_e32 v78, v46, v77
	v_mul_f32_e32 v79, v47, v77
	v_rndne_f32_e32 v75, v75
	v_cvt_i32_f32_e32 v76, v76
	v_rndne_f32_e32 v78, v78
	v_rndne_f32_e32 v79, v79
	v_cvt_i32_f32_e32 v75, v75
	v_cvt_i32_f32_sdwa v78, v78 dst_sel:WORD_1 dst_unused:UNUSED_PAD src0_sel:DWORD
	v_cvt_i32_f32_e32 v79, v79
	v_lshlrev_b32_e32 v76, 8, v76
	v_and_b32_e32 v76, 0xff00, v76
	v_and_b32_e32 v78, 0xff0000, v78
	v_perm_b32 v75, v79, v75, s3
	v_or3_b32 v75, v75, v76, v78
	v_mul_f32_e32 v78, v49, v77
	v_mul_f32_e32 v76, v48, v77
	v_rndne_f32_e32 v78, v78
	v_mul_f32_e32 v79, v50, v77
	v_mul_f32_e32 v80, v51, v77
	v_rndne_f32_e32 v76, v76
	v_cvt_i32_f32_e32 v78, v78
	v_rndne_f32_e32 v79, v79
	v_rndne_f32_e32 v80, v80
	v_cvt_i32_f32_e32 v76, v76
	v_cvt_i32_f32_sdwa v79, v79 dst_sel:WORD_1 dst_unused:UNUSED_PAD src0_sel:DWORD
	v_cvt_i32_f32_e32 v80, v80
	v_lshlrev_b32_e32 v78, 8, v78
	v_and_b32_e32 v78, 0xff00, v78
	v_and_b32_e32 v79, 0xff0000, v79
	v_perm_b32 v76, v80, v76, s3
	v_or3_b32 v76, v76, v78, v79
	v_mul_f32_e32 v79, v53, v77
	v_mul_f32_e32 v78, v52, v77
	v_rndne_f32_e32 v79, v79
	v_mul_f32_e32 v80, v54, v77
	v_mul_f32_e32 v77, v55, v77
	v_rndne_f32_e32 v78, v78
	v_cvt_i32_f32_e32 v79, v79
	v_rndne_f32_e32 v80, v80
	v_rndne_f32_e32 v77, v77
	v_cvt_i32_f32_e32 v78, v78
	v_cvt_i32_f32_sdwa v80, v80 dst_sel:WORD_1 dst_unused:UNUSED_PAD src0_sel:DWORD
	v_cvt_i32_f32_e32 v77, v77
	v_lshl_add_u64 v[72:73], s[56:57], 0, v[56:57]
	v_lshlrev_b32_e32 v79, 8, v79
	v_add_co_u32_e32 v72, vcc, 0x4000000, v72
	v_and_b32_e32 v79, 0xff00, v79
	v_and_b32_e32 v80, 0xff0000, v80
	v_perm_b32 v77, v77, v78, s3
	v_addc_co_u32_e32 v73, vcc, 0, v73, vcc
	v_or3_b32 v77, v77, v79, v80
	global_store_dwordx2 v[72:73], v[74:75], off
	global_store_dwordx2 v[72:73], v[76:77], off offset:512
	s_and_saveexec_b64 s[4:5], s[36:37]
	s_cbranch_execz .LBB0_980
	v_readlane_b32 s44, v252, 1
	v_readlane_b32 s58, v252, 15
	v_readlane_b32 s59, v252, 16
	s_add_u32 s18, s58, s7
	s_addc_u32 s19, s59, s10
	s_add_u32 s20, s58, s11
	v_readlane_b32 s45, v252, 2
	v_readlane_b32 s46, v252, 3
	v_readlane_b32 s47, v252, 4
	v_readlane_b32 s48, v252, 5
	v_readlane_b32 s49, v252, 6
	v_readlane_b32 s50, v252, 7
	v_readlane_b32 s51, v252, 8
	v_readlane_b32 s52, v252, 9
	v_readlane_b32 s53, v252, 10
	v_readlane_b32 s54, v252, 11
	v_readlane_b32 s55, v252, 12
	v_readlane_b32 s56, v252, 13
	v_readlane_b32 s57, v252, 14
	s_addc_u32 s21, s59, s14
	global_store_dword v65, v64, s[18:19]
	global_store_dwordx2 v65, v[240:241], s[20:21]
